# plus: P4b next-tile K/V loads batched and issued early; attention unit prologues overlap Q loads with first tiles
# speedup vs baseline: 1.0022x; 1.0022x over previous
; #define RAW_WAIT_BARRIER(n) do { asm volatile("s_waitcnt vmcnt(" #n ") lgkmcnt(0)" ::: "memory"); __builtin_amdgcn_s_barrier(); } while (0)
; DI void attn64_fixed256(const u16* __restrict__ Q, int ldq, const u16* __restrict__ Kb, int ldk, const u16* __restrict__ Vt, int ldv,
;                         int nkeys, u16* __restrict__ O, int ldo, float* ssq, int ssq_ld, u16* smem) {
;   const int tid = threadIdx.x, lane = tid & 63, w = __builtin_amdgcn_readfirstlane(tid >> 6), r = lane & 31, h = lane >> 5;
;   bf16x8 qf0[4], qf1[4];
;   {
;     const unsigned qo = (unsigned)((64 * w + r) * ldq + 8 * h);
; #pragma unroll
;     for (int ks = 0; ks < 4; ++ks) {
;       qf0[ks] = *(const bf16x8*)(Q + (size_t)(qo + ks * 16));
;       qf1[ks] = *(const bf16x8*)(Q + (size_t)(qo + 32 * ldq + ks * 16));
;     }
;   }
;   const int ntiles = nkeys / 64;
;   asm volatile("s_waitcnt vmcnt(0)" ::: "memory");
; #pragma unroll
;   for (int st = 0; st < 3; ++st) {
;     const int kb = st * 64;
;     glds_rows128(Kb + (size_t)kb * ldk, ldk, smem + st * A_STAGE, w, lane);
;     glds_rows128(Vt + kb, ldv, smem + st * A_STAGE + 4096, w, lane);
;   }
;   f32x16 O0[2], O1[2];
;   O0[0] = zero16(); O0[1] = zero16(); O1[0] = zero16(); O1[1] = zero16();
;   float l0 = 0.f, l1 = 0.f;
;   const int swz = (r >> 1) & 7;
;   for (int it = 0; it < ntiles; ++it) {
;     RAW_WAIT_BARRIER(8);
.LBB0_235:
	s_lshl_b32 s25, s25, 8
	s_ashr_i32 s37, s24, 2
	s_ashr_i32 s31, s30, 31
	s_ashr_i32 s26, s25, 31
	s_add_u32 s28, s30, s25
	s_addc_u32 s29, s31, s26
	s_lshl_b64 s[26:27], s[28:29], 10
	s_add_u32 s25, s56, s26
	s_addc_u32 s34, s57, s27
	s_lshl_b32 s26, s24, 6
	s_ashr_i32 s27, s26, 31
	s_lshl_b64 s[26:27], s[26:27], 1
	s_add_u32 s38, s25, s26
	s_addc_u32 s39, s34, s27
	s_lshl_b64 s[34:35], s[30:31], 8
	s_add_u32 s25, s58, s34
	s_addc_u32 s40, s59, s35
	s_lshl_b32 s30, s37, 6
	s_ashr_i32 s31, s30, 31
	s_lshl_b64 s[30:31], s[30:31], 1
	s_add_u32 s30, s25, s30
	s_addc_u32 s31, s40, s31
	s_add_u32 s25, s60, s34
	s_addc_u32 s40, s61, s35
	s_mul_hi_i32 s35, s37, s22
	s_mul_i32 s34, s37, s22
	s_lshl_b64 s[34:35], s[34:35], 7
	s_add_u32 s34, s25, s34
	v_readfirstlane_b32 s25, v188
	s_addc_u32 s35, s40, s35
	s_and_b32 s37, s25, 0xffffffc0
	v_or_b32_e32 v177, s37, v201
	v_lshl_or_b32 v164, v177, 9, v170
	v_or_b32_e32 v2, 0x4000, v164
	v_mov_b32_e32 v3, v165
	v_lshl_add_u64 v[0:1], v[164:165], 1, s[38:39]
	v_lshl_add_u64 v[2:3], v[2:3], 1, s[38:39]
	v_or_b32_e32 v4, 0x4010, v164
	v_mov_b32_e32 v5, v165
	global_load_dwordx4 v[128:131], v[0:1], off
	global_load_dwordx4 v[132:135], v[0:1], off offset:32
	v_lshl_add_u64 v[4:5], v[4:5], 1, s[38:39]
	global_load_dwordx4 v[136:139], v[2:3], off
	global_load_dwordx4 v[140:143], v[4:5], off
	v_or_b32_e32 v2, 0x4020, v164
	v_mov_b32_e32 v3, v165
	v_or_b32_e32 v164, 0x4030, v164
	v_lshl_add_u64 v[2:3], v[2:3], 1, s[38:39]
	global_load_dwordx4 v[144:147], v[0:1], off offset:64
	global_load_dwordx4 v[148:151], v[0:1], off offset:96
	v_lshl_add_u64 v[0:1], v[164:165], 1, s[38:39]
	s_lshr_b32 s25, s25, 6
	global_load_dwordx4 v[152:155], v[2:3], off
	global_load_dwordx4 v[156:159], v[0:1], off
	v_lshl_or_b32 v1, s25, 3, v171
	v_lshrrev_b32_e32 v0, 1, v1
	s_add_i32 s37, s25, 4
	v_xor_b32_e32 v0, v0, v188
	v_lshl_or_b32 v4, s37, 3, v171
	v_lshlrev_b32_e32 v0, 3, v0
	v_lshrrev_b32_e32 v2, 1, v4
	v_and_b32_e32 v3, 56, v0
	v_xor_b32_e32 v2, v2, v188
	v_lshl_or_b32 v0, v1, 7, v3
	v_lshlrev_b32_e32 v2, 3, v2
	v_mul_lo_u32 v1, v1, s22
	v_and_b32_e32 v5, 56, v2
	v_or_b32_e32 v164, v3, v1
	v_mul_lo_u32 v1, v4, s22
	s_lshl_b32 s40, s25, 9
	v_lshl_or_b32 v2, v4, 7, v5
	v_or_b32_e32 v168, v5, v1
	v_lshlrev_b32_e32 v4, 1, v0
	v_mov_b32_e32 v5, v165
	s_lshl_b32 s25, s25, 10
	v_lshl_add_u64 v[6:7], s[30:31], 0, v[4:5]
	s_mov_b32 m0, s25
	s_lshl_b32 s41, s37, 9
	global_load_lds_dwordx4 v[6:7], off
	v_lshlrev_b32_e32 v6, 1, v2
	v_mov_b32_e32 v7, v165
	s_lshl_b32 s37, s37, 10
	v_lshl_add_u64 v[8:9], s[30:31], 0, v[6:7]
	s_mov_b32 m0, s37
	v_mov_b32_e32 v169, v165
	global_load_lds_dwordx4 v[8:9], off
	v_lshl_add_u64 v[8:9], v[164:165], 1, s[34:35]
	s_add_i32 m0, s25, 0x2000
	v_lshl_add_u64 v[10:11], v[168:169], 1, s[34:35]
	global_load_lds_dwordx4 v[8:9], off
	s_add_i32 m0, s37, 0x2000
	s_add_u32 s38, s30, 0x4000
	s_addc_u32 s39, s31, 0
	global_load_lds_dwordx4 v[10:11], off
	v_lshl_add_u64 v[12:13], s[38:39], 0, v[4:5]
	s_add_i32 m0, s25, 0x4000
	v_mov_b32_e32 v32, 0
	global_load_lds_dwordx4 v[12:13], off
	v_lshl_add_u64 v[12:13], s[38:39], 0, v[6:7]
	s_add_i32 m0, s37, 0x4000
	v_lshlrev_b32_e32 v178, 1, v0
	global_load_lds_dwordx4 v[12:13], off
	v_lshl_add_u64 v[12:13], v[8:9], 0, s[10:11]
	s_add_i32 m0, s25, 0x6000
	v_lshlrev_b32_e32 v179, 1, v2
	global_load_lds_dwordx4 v[12:13], off
	s_add_i32 m0, s37, 0x6000
	s_add_u32 s38, s30, 0x8000
	v_lshl_add_u64 v[12:13], v[10:11], 0, s[10:11]
	s_addc_u32 s39, s31, 0
	global_load_lds_dwordx4 v[12:13], off
	v_lshl_add_u64 v[4:5], s[38:39], 0, v[4:5]
	s_add_i32 m0, s25, 0x8000
	s_lshr_b32 s22, s22, 6
	global_load_lds_dwordx4 v[4:5], off
	v_lshl_add_u64 v[4:5], s[38:39], 0, v[6:7]
	s_add_i32 m0, s37, 0x8000
	s_lshl_b32 s38, s22, 13
	global_load_lds_dwordx4 v[4:5], off
	v_lshl_add_u64 v[4:5], v[8:9], 0, s[20:21]
	s_add_i32 m0, s25, 0xa000
	s_mov_b32 s25, 3
	global_load_lds_dwordx4 v[4:5], off
	v_lshl_add_u64 v[4:5], v[10:11], 0, s[20:21]
	s_add_i32 m0, s37, 0xa000
	s_add_i32 s37, s22, -1
	global_load_lds_dwordx4 v[4:5], off
	s_mov_b32 s39, 0
	s_lshl_b32 s40, s40, 1
	s_lshl_b32 s41, s41, 1
	v_mov_b32_e32 v33, v32
	v_mov_b32_e32 v34, v32
	v_mov_b32_e32 v35, v32
	v_mov_b32_e32 v36, v32
	v_mov_b32_e32 v37, v32
	v_mov_b32_e32 v38, v32
	v_mov_b32_e32 v39, v32
	v_mov_b32_e32 v40, v32
	v_mov_b32_e32 v41, v32
	v_mov_b32_e32 v42, v32
	v_mov_b32_e32 v43, v32
	v_mov_b32_e32 v44, v32
	v_mov_b32_e32 v45, v32
	v_mov_b32_e32 v46, v32
	v_mov_b32_e32 v47, v32
	v_mov_b32_e32 v48, v32
	v_mov_b32_e32 v49, v32
	v_mov_b32_e32 v50, v32
	v_mov_b32_e32 v51, v32
	v_mov_b32_e32 v52, v32
	v_mov_b32_e32 v53, v32
	v_mov_b32_e32 v54, v32
	v_mov_b32_e32 v55, v32
	v_mov_b32_e32 v56, v32
	v_mov_b32_e32 v57, v32
	v_mov_b32_e32 v58, v32
	v_mov_b32_e32 v59, v32
	v_mov_b32_e32 v60, v32
	v_mov_b32_e32 v61, v32
	v_mov_b32_e32 v62, v32
	v_mov_b32_e32 v63, v32
	v_mov_b32_e32 v0, v32
	v_mov_b32_e32 v1, v32
	v_mov_b32_e32 v2, v32
	v_mov_b32_e32 v3, v32
	v_mov_b32_e32 v4, v32
	v_mov_b32_e32 v5, v32
	v_mov_b32_e32 v6, v32
	v_mov_b32_e32 v7, v32
	v_mov_b32_e32 v8, v32
	v_mov_b32_e32 v9, v32
	v_mov_b32_e32 v10, v32
	v_mov_b32_e32 v11, v32
	v_mov_b32_e32 v12, v32
	v_mov_b32_e32 v13, v32
	v_mov_b32_e32 v14, v32
	v_mov_b32_e32 v15, v32
	v_mov_b32_e32 v16, v32
	v_mov_b32_e32 v17, v32
	v_mov_b32_e32 v18, v32
	v_mov_b32_e32 v19, v32
	v_mov_b32_e32 v20, v32
	v_mov_b32_e32 v21, v32
	v_mov_b32_e32 v22, v32
	v_mov_b32_e32 v23, v32
	v_mov_b32_e32 v24, v32
	v_mov_b32_e32 v25, v32
	v_mov_b32_e32 v26, v32
	v_mov_b32_e32 v27, v32
	v_mov_b32_e32 v28, v32
	v_mov_b32_e32 v29, v32
	v_mov_b32_e32 v30, v32
	v_mov_b32_e32 v31, v32
	v_mov_b32_e32 v166, v32
	v_mov_b32_e32 v167, v32
	v_mov_b32_e32 v191, 0
	v_mov_b32_e32 v252, 0
	s_min_u32 s44, s25, s37
	s_add_i32 s22, s39, 0x6000
	s_and_b32 s42, s22, 0x6000
	s_lshl_b32 s22, s44, 6
	s_lshl_b32 s45, s42, 1
	s_lshl_b64 s[42:43], s[22:23], 8
	s_add_u32 s42, s30, s42
	s_addc_u32 s43, s31, s43
	s_add_i32 s22, s45, s40
	s_add_i32 s46, s45, s41
	s_lshl_b32 s44, s44, 7
	s_add_u32 s44, s34, s44
	s_addc_u32 s45, s35, 0
	s_and_b32 s47, s39, 0x6000
	v_lshl_or_b32 v160, s47, 1, v172
	v_add_u32_e32 v161, v160, v174
	v_add_u32_e32 v162, v160, v175
	v_add_u32_e32 v163, v160, v176
	v_add_u32_e32 v160, v160, v173
	s_mov_b32 m0, s22
	s_waitcnt vmcnt(8) lgkmcnt(0)
	s_barrier
; #define MFMA32(a, b, c) __builtin_amdgcn_mfma_f32_32x32x16_bf16((a), (b), (c), 0, 0, 0)
; DI void attn64_fixed256(const u16* __restrict__ Q, int ldq, const u16* __restrict__ Kb, int ldk, const u16* __restrict__ Vt, int ldv,
;                         int nkeys, u16* __restrict__ O, int ldo, float* ssq, int ssq_ld, u16* smem) {
;     ...
;     {
;       const int itn = it + 3 < ntiles ? it + 3 : ntiles - 1;
;       u16* dst = smem + ((it + 3) & 3) * A_STAGE;
;       glds_rows128(Kb + (size_t)(itn * 64) * ldk, ldk, dst, w, lane);
;       glds_rows128(Vt + itn * 64, ldv, dst + 4096, w, lane);
;     }
;     const u16* sK = smem + (it & 3) * A_STAGE;
;     const u16* sV = sK + 4096;
;     f32x16 S0[2], S1[2];
; #pragma unroll
;     for (int kt = 0; kt < 2; ++kt) {
;       S0[kt] = zero16(); S1[kt] = zero16();
; #pragma unroll
;       for (int ks = 0; ks < 4; ++ks) {
;         const bf16x8 kf = *(const bf16x8*)(sK + (kt * 32 + r) * 64 + (((2 * ks + h) ^ swz) * 8));
;         S0[kt] = MFMA32(kf, qf0[ks], S0[kt]);
;         S1[kt] = MFMA32(kf, qf1[ks], S1[kt]);
;       }
;     }
;     ...
;     A256_SOFTMAX_PV(S0, O0, l0)
;     A256_SOFTMAX_PV(S1, O1, l1)
	ds_read_b128 v[212:215], v160
	ds_read_b128 v[216:219], v161
	ds_read_b128 v[220:223], v162
	ds_read_b128 v[224:227], v163
	global_load_lds_dwordx4 v178, s[42:43]
	s_mov_b32 m0, s46
	s_nop 0
	global_load_lds_dwordx4 v179, s[42:43]
	s_add_i32 m0, s22, 0x2000
	v_lshl_add_u64 v[192:193], v[164:165], 1, s[44:45]
	global_load_lds_dwordx4 v[192:193], off
	s_add_i32 m0, s46, 0x2000
	s_nop 0
	v_lshl_add_u64 v[196:197], v[168:169], 1, s[44:45]
	global_load_lds_dwordx4 v[196:197], off
	s_waitcnt lgkmcnt(0)
	v_mfma_f32_32x32x16_bf16 v[112:127], v[212:215], v[128:131], 0
	ds_read_b128 v[228:231], v160 offset:8192
	ds_read_b128 v[232:235], v160 offset:12288
	ds_read_b128 v[236:239], v161 offset:8192
	ds_read_b128 v[240:243], v161 offset:12288
	v_mfma_f32_32x32x16_bf16 v[112:127], v[216:219], v[132:135], v[112:127]
	v_mfma_f32_32x32x16_bf16 v[112:127], v[220:223], v[144:147], v[112:127]
	v_mfma_f32_32x32x16_bf16 v[112:127], v[224:227], v[148:151], v[112:127]
	v_mfma_f32_32x32x16_bf16 v[96:111], v[212:215], v[136:139], 0
	v_mfma_f32_32x32x16_bf16 v[96:111], v[216:219], v[140:143], v[96:111]
	v_mfma_f32_32x32x16_bf16 v[96:111], v[220:223], v[152:155], v[96:111]
	v_mfma_f32_32x32x16_bf16 v[96:111], v[224:227], v[156:159], v[96:111]
	s_nop 7
	ds_read_b128 v[212:215], v160 offset:4096
	ds_read_b128 v[216:219], v161 offset:4096
	ds_read_b128 v[220:223], v162 offset:4096
	ds_read_b128 v[224:227], v163 offset:4096
	v_exp_f32_e32 v112, v112
	v_exp_f32_e32 v113, v113
	v_exp_f32_e32 v114, v114
	v_exp_f32_e32 v115, v115
	v_add_f32_e32 v166, v166, v112
	v_add_f32_e32 v191, v191, v113
	v_exp_f32_e32 v116, v116
	v_exp_f32_e32 v117, v117
	v_add_f32_e32 v166, v166, v114
	v_add_f32_e32 v191, v191, v115
	v_cvt_pk_bf16_f32 v112, v112, v113
	v_exp_f32_e32 v118, v118
	v_exp_f32_e32 v119, v119
	v_add_f32_e32 v166, v166, v116
	v_add_f32_e32 v191, v191, v117
	v_cvt_pk_bf16_f32 v113, v114, v115
	v_exp_f32_e32 v96, v96
	v_exp_f32_e32 v97, v97
	v_add_f32_e32 v166, v166, v118
	v_add_f32_e32 v191, v191, v119
	v_cvt_pk_bf16_f32 v114, v116, v117
	v_exp_f32_e32 v98, v98
	v_exp_f32_e32 v99, v99
	v_add_f32_e32 v167, v167, v96
	v_add_f32_e32 v252, v252, v97
	v_cvt_pk_bf16_f32 v115, v118, v119
	v_exp_f32_e32 v100, v100
	v_exp_f32_e32 v101, v101
	v_add_f32_e32 v167, v167, v98
	v_add_f32_e32 v252, v252, v99
	v_cvt_pk_bf16_f32 v96, v96, v97
	v_exp_f32_e32 v102, v102
	v_exp_f32_e32 v103, v103
	v_add_f32_e32 v167, v167, v100
	v_add_f32_e32 v252, v252, v101
	v_cvt_pk_bf16_f32 v97, v98, v99
	s_waitcnt lgkmcnt(0)
	v_mfma_f32_32x32x16_bf16 v[80:95], v[212:215], v[128:131], 0
	ds_read_b128 v[244:247], v162 offset:8192
	ds_read_b128 v[248:251], v162 offset:12288
	ds_read_b128 v[180:183], v163 offset:8192
	ds_read_b128 v[184:187], v163 offset:12288
	v_exp_f32_e32 v120, v120
	v_exp_f32_e32 v121, v121
	v_add_f32_e32 v167, v167, v102
	v_add_f32_e32 v252, v252, v103
	v_cvt_pk_bf16_f32 v98, v100, v101
	v_mfma_f32_32x32x16_bf16 v[80:95], v[216:219], v[132:135], v[80:95]
	v_exp_f32_e32 v122, v122
	v_exp_f32_e32 v123, v123
	v_add_f32_e32 v166, v166, v120
	v_add_f32_e32 v191, v191, v121
	v_cvt_pk_bf16_f32 v99, v102, v103
	v_mfma_f32_32x32x16_bf16 v[80:95], v[220:223], v[144:147], v[80:95]
	v_exp_f32_e32 v124, v124
	v_exp_f32_e32 v125, v125
	v_add_f32_e32 v166, v166, v122
	v_add_f32_e32 v191, v191, v123
	v_cvt_pk_bf16_f32 v120, v120, v121
	v_mfma_f32_32x32x16_bf16 v[80:95], v[224:227], v[148:151], v[80:95]
	v_exp_f32_e32 v126, v126
	v_exp_f32_e32 v127, v127
	v_add_f32_e32 v166, v166, v124
	v_add_f32_e32 v191, v191, v125
	v_cvt_pk_bf16_f32 v121, v122, v123
	v_mfma_f32_32x32x16_bf16 v[64:79], v[212:215], v[136:139], 0
	v_exp_f32_e32 v104, v104
	v_exp_f32_e32 v105, v105
	v_add_f32_e32 v166, v166, v126
	v_add_f32_e32 v191, v191, v127
	v_cvt_pk_bf16_f32 v122, v124, v125
	v_mfma_f32_32x32x16_bf16 v[64:79], v[216:219], v[140:143], v[64:79]
	v_exp_f32_e32 v106, v106
	v_exp_f32_e32 v107, v107
	v_add_f32_e32 v167, v167, v104
	v_add_f32_e32 v252, v252, v105
	v_cvt_pk_bf16_f32 v123, v126, v127
	v_mfma_f32_32x32x16_bf16 v[64:79], v[220:223], v[152:155], v[64:79]
	v_exp_f32_e32 v108, v108
	v_exp_f32_e32 v109, v109
	v_add_f32_e32 v167, v167, v106
	v_add_f32_e32 v252, v252, v107
	v_cvt_pk_bf16_f32 v104, v104, v105
	v_mfma_f32_32x32x16_bf16 v[64:79], v[224:227], v[156:159], v[64:79]
	v_exp_f32_e32 v110, v110
	v_exp_f32_e32 v111, v111
	v_add_f32_e32 v167, v167, v108
	v_add_f32_e32 v252, v252, v109
	v_cvt_pk_bf16_f32 v105, v106, v107
	s_addk_i32 s39, 0x2000
	s_add_i32 s25, s25, 1

; template <bool WIN, bool FIXEDM> ...
;   const int tid = threadIdx.x, lane = tid & 63, w = __builtin_amdgcn_readfirstlane(tid >> 6), r = lane & 31, h = lane >> 5;
;   bf16x8 qf[4];
;   {
;     const unsigned qo = (unsigned)((32 * w + r) * ldq + 8 * h);
; #pragma unroll
;     for (int ks = 0; ks < 4; ++ks) qf[ks] = *(const bf16x8*)(Q + (size_t)(qo + ks * 16));
;   }
;   const int ntiles = (kend - kbeg) / 64;
;   asm volatile("s_waitcnt vmcnt(0)" ::: "memory");
; #pragma unroll
;   for (int st = 0; st < 3; ++st) {
;     const int kb = kbeg + st * 64;
;     glds_rows128(Kb + (size_t)kb * ldk, ldk, smem + st * A_STAGE, w, lane);
;     glds_rows128(Vt + kb, ldv, smem + st * A_STAGE + 4096, w, lane);
;   }
;   f32x16 Oacc[2];
;   Oacc[0] = zero16(); Oacc[1] = zero16();
;   float mrow = m_init;
;   float lrow = WIN ? (h == 0 ? (FIXEDM ? lsink : 1.f) : 0.f) : 0.f;
;   const int swz = (r >> 1) & 7;
;   const int qrow = q0 + 32 * w + r - 4 * h;
;   const float sinit = FIXEDM ? -m_init : 0.f;
; DI void phase2(const Params& p, u16* smem) {
;     ...
;       int kbeg = q0 - 128; if (kbeg < 0) kbeg = 0;
;       int kend = q0 + 256; if (kend > S) kend = S;
;       const float sink2 = p.sink_a[head] * LOG2E;
;       const u16* Qp = qa + tq * 512 + head * 64; const u16* Kp = ka + (size_t)seq_tok0 * 128 + kvh * 64;
;       const u16* Vp = vta + (size_t)seq_tok0 * 128 + (size_t)kvh * 64 * S;
;       u16* Op = oab + tq * 1024 + head * 64; float* Sp = ssq + tq * 16 + head;
;       const float mfix = fmaxf(bnd, sink2);
;       if (fixedm && mfix <= 40.0f) attn64_glds<true, true>(Qp, 512, Kp, 128, Vp, S, kbeg, kend, q0, mfix, exp2f(sink2 - mfix), cexp, Op, 1024, Sp, 16, smem);
;       else attn64_glds<true, false>(Qp, 512, Kp, 128, Vp, S, kbeg, kend, q0, sink2, 0.f, cexp, Op, 1024, Sp, 16, smem);
.LBB0_259:
	s_and_b64 vcc, exec, s[52:53]
	s_cbranch_vccz .LBB0_268
	v_sub_f32_e32 v20, v121, v156
	v_cmp_gt_f32_e32 vcc, s75, v20
	s_and_b64 s[8:9], vcc, exec
	v_readfirstlane_b32 s8, v188
	s_cselect_b32 s83, 0xffffffc0, 0
	s_lshr_b32 s9, s8, 6
	s_lshl_b32 s8, s9, 5
	v_or_b32_e32 v154, s8, v201
	v_lshl_or_b32 v0, v154, 10, v145
	global_load_dwordx4 v[112:115], v0, s[48:49]
	global_load_dwordx4 v[116:119], v0, s[48:49] offset:32
	global_load_dwordx4 v[120:123], v0, s[48:49] offset:64
	global_load_dwordx4 v[124:127], v0, s[48:49] offset:96
	v_lshl_or_b32 v0, s9, 3, v191
	s_add_i32 s49, s9, 4
	s_waitcnt lgkmcnt(0)
	v_lshrrev_b32_e32 v1, 1, v0
	v_lshl_or_b32 v3, s49, 3, v191
	v_xor_b32_e32 v1, v1, v188
	v_lshrrev_b32_e32 v4, 1, v3
	v_lshlrev_b32_e32 v1, 3, v1
	v_xor_b32_e32 v4, v4, v188
	s_mov_b32 s47, s21
	s_sub_i32 s48, s82, s46
	v_and_b32_e32 v1, 56, v1
	v_lshlrev_b32_e32 v4, 3, v4
	s_lshl_b64 s[50:51], s[46:47], 8
	v_lshl_or_b32 v2, v0, 7, v1
	v_and_b32_e32 v4, 56, v4
	s_add_u32 s50, s37, s50
	v_lshl_or_b32 v5, v3, 7, v4
	v_mul_lo_u32 v0, v0, s76
	s_addc_u32 s51, s78, s51
	v_lshlrev_b32_e32 v130, 1, v2
	v_mov_b32_e32 v131, v129
	s_lshl_b32 s82, s9, 10
	v_or_b32_e32 v128, v1, v0
	v_mul_lo_u32 v0, v3, s76
	v_lshl_add_u64 v[2:3], s[50:51], 0, v[130:131]
	s_mov_b32 m0, s82
	v_lshlrev_b32_e32 v132, 1, v5
	v_mov_b32_e32 v133, v129
	global_load_lds_dwordx4 v[2:3], off
	v_lshl_add_u64 v[2:3], s[50:51], 0, v[132:133]
	s_lshl_b32 s84, s49, 10
	s_lshl_b64 s[50:51], s[46:47], 1
	v_or_b32_e32 v0, v4, v0
	v_mov_b32_e32 v1, v129
	s_add_u32 s50, s79, s50
	s_mov_b32 m0, s84
	s_addc_u32 s51, s80, s51
	v_lshlrev_b64 v[134:135], 1, v[128:129]
	v_lshlrev_b64 v[136:137], 1, v[0:1]
	global_load_lds_dwordx4 v[2:3], off
	v_lshl_add_u64 v[2:3], s[50:51], 0, v[134:135]
	s_add_i32 m0, s82, 0x2000
	v_lshl_add_u64 v[0:1], s[50:51], 0, v[136:137]
	s_sub_i32 s50, s20, 64
	s_mov_b32 s51, s21
	global_load_lds_dwordx4 v[2:3], off
	s_add_i32 m0, s84, 0x2000
	s_lshl_b64 s[52:53], s[50:51], 8
	s_add_u32 s52, s37, s52
	s_addc_u32 s53, s78, s53
	global_load_lds_dwordx4 v[0:1], off
	v_lshl_add_u64 v[0:1], s[52:53], 0, v[130:131]
	s_add_i32 m0, s82, 0x4000
	s_lshl_b64 s[50:51], s[50:51], 1
	global_load_lds_dwordx4 v[0:1], off
	s_add_i32 m0, s84, 0x4000
	s_add_u32 s50, s79, s50
	v_lshl_add_u64 v[0:1], s[52:53], 0, v[132:133]
	s_addc_u32 s51, s80, s51
	global_load_lds_dwordx4 v[0:1], off
	v_lshl_add_u64 v[0:1], s[50:51], 0, v[134:135]
	s_add_i32 m0, s82, 0x6000
	v_xor_b32_e32 v32, 0x80000000, v156
	global_load_lds_dwordx4 v[0:1], off
	v_lshl_add_u64 v[0:1], s[50:51], 0, v[136:137]
	s_add_i32 m0, s84, 0x6000
	s_lshl_b64 s[50:51], s[20:21], 8
	s_add_u32 s50, s37, s50
	s_addc_u32 s51, s78, s51
	global_load_lds_dwordx4 v[0:1], off
	v_lshl_add_u64 v[0:1], s[50:51], 0, v[130:131]
	s_add_i32 m0, s82, 0x8000
	s_lshl_b32 s47, s20, 1
	global_load_lds_dwordx4 v[0:1], off
	s_add_i32 m0, s84, 0x8000
	v_lshl_add_u64 v[0:1], s[50:51], 0, v[132:133]
	s_add_u32 s50, s79, s47
	s_addc_u32 s51, s80, 0
	global_load_lds_dwordx4 v[0:1], off
	v_lshl_add_u64 v[0:1], s[50:51], 0, v[134:135]
	s_add_i32 m0, s82, 0xa000
	v_mov_b32_e32 v33, v32
	global_load_lds_dwordx4 v[0:1], off
	v_lshl_add_u64 v[0:1], s[50:51], 0, v[136:137]
	s_add_i32 m0, s84, 0xa000
	v_mov_b32_e32 v34, v32
	global_load_lds_dwordx4 v[0:1], off
	s_waitcnt vmcnt(8) lgkmcnt(0)
	s_barrier
	ds_read_b128 v[0:3], v146
	ds_read_b128 v[4:7], v146 offset:4096
	v_mov_b32_e32 v35, v32
	v_mov_b32_e32 v36, v32
	v_mov_b32_e32 v37, v32
	v_mov_b32_e32 v38, v32
	v_mov_b32_e32 v39, v32
	v_mov_b32_e32 v40, v32
	v_mov_b32_e32 v41, v32
	v_mov_b32_e32 v42, v32
	v_mov_b32_e32 v43, v32
	v_mov_b32_e32 v44, v32
	v_mov_b32_e32 v45, v32
	v_mov_b32_e32 v46, v32
	v_mov_b32_e32 v47, v32
	v_cndmask_b32_e32 v21, 0, v153, vcc
	v_mov_b32_e32 v31, 0
	s_waitcnt lgkmcnt(0)
	v_mfma_f32_32x32x16_bf16 v[64:79], v[0:3], v[112:115], v[32:47]
	ds_read_b128 v[0:3], v147
	ds_read_b128 v[8:11], v147 offset:4096
	s_cmp_lt_i32 s48, 64
	v_mfma_f32_32x32x16_bf16 v[48:63], v[4:7], v[112:115], v[32:47]
	s_waitcnt lgkmcnt(1)
	v_mfma_f32_32x32x16_bf16 v[64:79], v[0:3], v[116:119], v[64:79]
	ds_read_b128 v[0:3], v148
	ds_read_b128 v[12:15], v148 offset:4096
	s_waitcnt lgkmcnt(2)
	v_mfma_f32_32x32x16_bf16 v[48:63], v[8:11], v[116:119], v[48:63]
	s_waitcnt lgkmcnt(1)
	v_mfma_f32_32x32x16_bf16 v[64:79], v[0:3], v[120:123], v[64:79]
	ds_read_b128 v[0:3], v149
	ds_read_b128 v[16:19], v149 offset:4096
	s_waitcnt lgkmcnt(2)
	v_mfma_f32_32x32x16_bf16 v[48:63], v[12:15], v[120:123], v[48:63]
	s_waitcnt lgkmcnt(1)
	v_mfma_f32_32x32x16_bf16 v[64:79], v[0:3], v[124:127], v[64:79]
	v_add_f32_e32 v0, v20, v21
	v_exp_f32_e32 v0, v0
	s_nop 0
	v_ldexp_f32 v0, v0, s83
	v_cndmask_b32_e64 v131, 0, v0, s[22:23]
	s_waitcnt lgkmcnt(0)
	v_mfma_f32_32x32x16_bf16 v[48:63], v[16:19], v[124:127], v[48:63]
	s_cbranch_scc1 .LBB0_266
	s_add_i32 s8, s8, s81
	v_add_u32_e32 v0, s8, v144
	s_lshl_b32 s9, s9, 9
	s_lshl_b32 s51, s49, 9
	s_bfe_i32 s47, s48, 0x100006
	v_subrev_u32_e32 v128, s20, v0
	v_mov_b32_e32 v0, 0
	s_add_i32 s48, s47, -1
	s_movk_i32 s49, 0x4000
	s_mov_b32 s52, 2
	s_lshl_b32 s50, s9, 1
	s_lshl_b32 s51, s51, 1
	v_mov_b32_e32 v1, v0
	v_mov_b32_e32 v2, v0
	v_mov_b32_e32 v3, v0
	v_mov_b32_e32 v4, v0
	v_mov_b32_e32 v5, v0
	v_mov_b32_e32 v6, v0
	v_mov_b32_e32 v7, v0
	v_mov_b32_e32 v8, v0
	v_mov_b32_e32 v9, v0
	v_mov_b32_e32 v10, v0
	v_mov_b32_e32 v11, v0
	v_mov_b32_e32 v12, v0
	v_mov_b32_e32 v13, v0
	v_mov_b32_e32 v14, v0
	v_mov_b32_e32 v15, v0
	v_mov_b32_e32 v16, v0
	v_mov_b32_e32 v17, v0
	v_mov_b32_e32 v18, v0
	v_mov_b32_e32 v19, v0
	v_mov_b32_e32 v20, v0
	v_mov_b32_e32 v21, v0
	v_mov_b32_e32 v22, v0
	v_mov_b32_e32 v23, v0
	v_mov_b32_e32 v24, v0
	v_mov_b32_e32 v25, v0
	v_mov_b32_e32 v26, v0
	v_mov_b32_e32 v27, v0
	v_mov_b32_e32 v28, v0
	v_mov_b32_e32 v29, v0
	v_mov_b32_e32 v30, v0
	v_mov_b32_e32 v31, v0
	s_branch .LBB0_264

; #define MFMA32(a, b, c) __builtin_amdgcn_mfma_f32_32x32x16_bf16((a), (b), (c), 0, 0, 0)
; template <int D, bool WIN> ...
;     ...
;   for (int it = 0; it < ntiles; ++it) {
;     const int st = it & 1;
;     const int kb = kbeg + it * 64;
;     GLOAD(kb + 64 < kend ? kb + 64 : kb)
;     f32x16 Sacc[2];
;     constexpr bool EARLY = (D == 64);
;     bf16x8 vfr[EARLY ? 8 : 1];
;     if constexpr (EARLY) {
;       bf16x8 kfr[2][NKS];
; #pragma unroll
;       for (int kt = 0; kt < 2; ++kt)
; #pragma unroll
;         for (int ks = 0; ks < NKS; ++ks) kfr[kt][ks] = *(const bf16x8*)(sKp(st) + (kt * 32 + r) * LK + ks * 16 + 8 * h);
; #pragma unroll
;       for (int kt = 0; kt < 2; ++kt) {
;         Sacc[kt] = zero16();
; #pragma unroll
;         for (int ks = 0; ks < NKS; ++ks) Sacc[kt] = MFMA32(kfr[kt][ks], qf[ks], Sacc[kt]);
;       }
; #pragma unroll
;       for (int kt = 0; kt < 2; ++kt)
; #pragma unroll
;         for (int s = 0; s < 2; ++s)
; #pragma unroll
;           for (int m = 0; m < NMT; ++m) {
;             const u16* vp = sVp(st) + (m * 32 + r) * LV + kt * 32 + 16 * s + 4 * h;
;             s16x4 lo = *(const s16x4*)vp;
;             s16x4 hi = *(const s16x4*)(vp + 8);
;             vfr[(kt * 2 + s) * 2 + (m & 1)] = __builtin_shufflevector(lo, hi, 0, 1, 2, 3, 4, 5, 6, 7);
;           }
;       __builtin_amdgcn_sched_barrier(0);
;     } else {
; #pragma unroll
;       for (int kt = 0; kt < 2; ++kt) {
;         Sacc[kt] = zero16();
; #pragma unroll
;         for (int ks = 0; ks < NKS; ++ks) {
;           bf16x8 a = *(const bf16x8*)(sKp(st) + (kt * 32 + r) * LK + ks * 16 + 8 * h);
;           Sacc[kt] = MFMA32(a, qf[ks], Sacc[kt]);
;         }
;       }
;     }
;     if (WIN) {
;       const int dl0 = q0 + 32 * w + r - kb - 4 * h;
; #pragma unroll
;       for (int kt = 0; kt < 2; ++kt)
; #pragma unroll
;         for (int i = 0; i < 16; ++i) {
;           const int dlt = dl0 - (kt * 32 + (i & 3) + 8 * (i >> 2));
;           bool ok = (dlt <= 128) && (dlt >= -128);
;           Sacc[kt][i] = ok ? Sacc[kt][i] : -1e30f;
;         }
;     }
;     float mx = Sacc[0][0];
; #pragma unroll
;     for (int kt = 0; kt < 2; ++kt)
; #pragma unroll
;       for (int i = 0; i < 16; ++i) mx = fmaxf(mx, Sacc[kt][i]);
;     mx = fmaxf(mx, __shfl_xor(mx, 32));
;     const float mnew = fmaxf(mrow, mx * cexp);
.LBB0_326:
	s_and_b32 s22, s24, 1
	s_cmpk_lg_i32 s25, 0x100
	s_cselect_b32 s8, s25, 0xc0
	v_or_b32_e32 v64, s8, v180
	v_lshlrev_b32_e32 v128, 10, v64
	v_lshl_add_u64 v[178:179], v[162:163], 0, v[128:129]
	v_add_lshl_u32 v128, s8, v181, 10
	v_lshl_add_u64 v[176:177], v[162:163], 0, v[128:129]
	v_add_lshl_u32 v128, s8, v182, 10
	v_lshl_add_u64 v[174:175], v[162:163], 0, v[128:129]
	v_add_lshl_u32 v128, s8, v183, 10
	s_lshl_b64 s[40:41], s[8:9], 1
	s_mul_i32 s8, s22, 0x8800
	s_xor_b32 s42, s22, 1
	s_mul_i32 s42, s42, 0x8800
	v_or_b32_e32 v64, s8, v197
	v_lshl_add_u64 v[172:173], v[162:163], 0, v[128:129]
	v_add_u32_e32 v128, v64, v210
	v_mov_b32_e32 v221, v68
	ds_read_b128 v[64:67], v128
	ds_read_b128 v[68:71], v128 offset:32
	s_waitcnt vmcnt(7) lgkmcnt(1)
	v_mfma_f32_32x32x16_bf16 v[80:95], v[64:67], v[96:99], 0
	ds_read_b128 v[64:67], v128 offset:64
	ds_read_b128 v[224:227], v128 offset:8736
	v_lshl_add_u64 v[170:171], v[152:153], 0, s[40:41]
	v_lshl_add_u64 v[168:169], v[154:155], 0, s[40:41]
	v_lshl_add_u64 v[166:167], v[156:157], 0, s[40:41]
	v_lshl_add_u64 v[164:165], v[158:159], 0, s[40:41]
	s_add_i32 s24, s24, 1
	s_waitcnt vmcnt(6) lgkmcnt(2)
	v_mfma_f32_32x32x16_bf16 v[80:95], v[68:71], v[100:103], v[80:95]
	s_add_i32 s25, s25, 64
	s_waitcnt vmcnt(5) lgkmcnt(1)
	v_mfma_f32_32x32x16_bf16 v[80:95], v[64:67], v[104:107], v[80:95]
	ds_read_b128 v[64:67], v128 offset:96
	s_waitcnt vmcnt(4) lgkmcnt(0)
	v_mfma_f32_32x32x16_bf16 v[80:95], v[64:67], v[108:111], v[80:95]
	ds_read_b128 v[64:67], v128 offset:128
	s_waitcnt vmcnt(3) lgkmcnt(0)
	v_mfma_f32_32x32x16_bf16 v[80:95], v[64:67], v[112:115], v[80:95]
	ds_read_b128 v[64:67], v128 offset:160
	s_waitcnt vmcnt(2) lgkmcnt(0)
	v_mfma_f32_32x32x16_bf16 v[80:95], v[64:67], v[116:119], v[80:95]
	ds_read_b128 v[64:67], v128 offset:192
	s_waitcnt vmcnt(1) lgkmcnt(0)
	v_mfma_f32_32x32x16_bf16 v[80:95], v[64:67], v[120:123], v[80:95]
	ds_read_b128 v[64:67], v128 offset:224
	s_waitcnt vmcnt(0) lgkmcnt(0)
	v_mfma_f32_32x32x16_bf16 v[80:95], v[64:67], v[124:127], v[80:95]
	global_load_dwordx4 v[236:239], v[178:179], off
	global_load_dwordx4 v[240:243], v[176:177], off
	global_load_dwordx4 v[244:247], v[174:175], off
	global_load_dwordx4 v[248:251], v[172:173], off
	ds_read_b128 v[64:67], v128 offset:8704
	s_waitcnt lgkmcnt(0)
	v_mfma_f32_32x32x16_bf16 v[64:79], v[64:67], v[96:99], 0
	s_nop 8
	v_max_f32_e32 v220, v80, v80
	v_mfma_f32_32x32x16_bf16 v[64:79], v[224:227], v[100:103], v[64:79]
	ds_read_b128 v[224:227], v128 offset:8768
	s_waitcnt lgkmcnt(0)
	v_mfma_f32_32x32x16_bf16 v[64:79], v[224:227], v[104:107], v[64:79]
	ds_read_b128 v[224:227], v128 offset:8800
	s_waitcnt lgkmcnt(0)
	v_mfma_f32_32x32x16_bf16 v[64:79], v[224:227], v[108:111], v[64:79]
	ds_read_b128 v[224:227], v128 offset:8832
	s_waitcnt lgkmcnt(0)
	v_mfma_f32_32x32x16_bf16 v[64:79], v[224:227], v[112:115], v[64:79]
	ds_read_b128 v[224:227], v128 offset:8864
	s_waitcnt lgkmcnt(0)
	v_mfma_f32_32x32x16_bf16 v[64:79], v[224:227], v[116:119], v[64:79]
	ds_read_b128 v[224:227], v128 offset:8896
	s_waitcnt lgkmcnt(0)
	v_mfma_f32_32x32x16_bf16 v[64:79], v[224:227], v[120:123], v[64:79]
	ds_read_b128 v[224:227], v128 offset:8928
	v_max_f32_e32 v128, v81, v81
	v_max_f32_e32 v128, v220, v128
	v_max3_f32 v128, v128, v82, v83
	v_max3_f32 v128, v128, v84, v85
	v_max3_f32 v128, v128, v86, v87
	v_max3_f32 v128, v128, v88, v89
	s_waitcnt lgkmcnt(0)
	v_mfma_f32_32x32x16_bf16 v[64:79], v[224:227], v[124:127], v[64:79]
	v_max3_f32 v128, v128, v90, v91
	v_max3_f32 v128, v128, v92, v93
	v_max3_f32 v128, v128, v94, v95
	s_nop 8
	v_max3_f32 v128, v128, v64, v65
	v_max3_f32 v128, v128, v66, v67
	v_max3_f32 v128, v128, v68, v69
	v_max3_f32 v128, v128, v70, v71
	v_max3_f32 v128, v128, v72, v73
	v_max3_f32 v128, v128, v74, v75
	v_max3_f32 v128, v128, v76, v77
	v_max3_f32 v128, v128, v78, v79
	ds_bpermute_b32 v220, v209, v128
	s_waitcnt lgkmcnt(0)
	v_max_f32_e32 v220, v220, v220
	v_max_f32_e32 v128, v128, v220
	v_mul_f32_e32 v128, 0x3e0293ee, v128
	v_max_f32_e32 v220, v222, v222
	v_max_f32_e32 v220, v220, v128
	v_fma_f32 v80, v80, s37, -v220
	v_sub_f32_e32 v128, v222, v220
	v_exp_f32_e32 v222, v80
	v_fma_f32 v81, v81, s37, -v220
	v_exp_f32_e32 v223, v81
	v_fma_f32 v81, v82, s37, -v220
	v_exp_f32_e32 v224, v81
	v_fma_f32 v81, v83, s37, -v220
	v_exp_f32_e32 v225, v81
	v_fma_f32 v81, v84, s37, -v220
	v_add_f32_e32 v80, 0, v222
	v_exp_f32_e32 v226, v81
	v_fma_f32 v81, v85, s37, -v220
	v_add_f32_e32 v80, v223, v80
	v_exp_f32_e32 v227, v81
	v_fma_f32 v81, v86, s37, -v220
	v_add_f32_e32 v80, v224, v80
	v_exp_f32_e32 v228, v81
	v_fma_f32 v81, v87, s37, -v220
	v_add_f32_e32 v80, v225, v80
	v_exp_f32_e32 v229, v81
	v_add_f32_e32 v80, v226, v80
	v_add_f32_e32 v80, v227, v80
	v_add_f32_e32 v80, v228, v80
	v_add_f32_e32 v81, v229, v80
	v_fma_f32 v80, v88, s37, -v220
	v_exp_f32_e32 v80, v80
	v_fma_f32 v87, v94, s37, -v220
	v_exp_f32_e32 v87, v87
	v_fma_f32 v88, v95, s37, -v220
	v_add_f32_e32 v82, v80, v81
	v_fma_f32 v81, v89, s37, -v220
	v_exp_f32_e32 v81, v81
	v_fma_f32 v64, v64, s37, -v220
	v_exp_f32_e32 v128, v128
	v_add_f32_e32 v83, v81, v82
	v_fma_f32 v82, v90, s37, -v220
	v_exp_f32_e32 v82, v82
	v_exp_f32_e32 v90, v88
	v_pk_mul_f32 v[62:63], v[62:63], v[128:129] op_sel_hi:[1,0]
	v_pk_mul_f32 v[60:61], v[60:61], v[128:129] op_sel_hi:[1,0]
	v_add_f32_e32 v84, v82, v83
	v_fma_f32 v83, v91, s37, -v220
	v_exp_f32_e32 v83, v83
	v_pk_mul_f32 v[58:59], v[58:59], v[128:129] op_sel_hi:[1,0]
	v_pk_mul_f32 v[56:57], v[56:57], v[128:129] op_sel_hi:[1,0]
	v_pk_mul_f32 v[54:55], v[54:55], v[128:129] op_sel_hi:[1,0]
	v_add_f32_e32 v85, v83, v84
	v_fma_f32 v84, v92, s37, -v220
; #define MFMA32(a, b, c) __builtin_amdgcn_mfma_f32_32x32x16_bf16((a), (b), (c), 0, 0, 0)
; #define LSTORE(stv) { const int st_ = (stv); KSTORE(0, kreg0) KSTORE(1, kreg1) KSTORE(2, kreg2) KSTORE(3, kreg3) \
;     VSTORE(0, vreg0) VSTORE(1, vreg1) VSTORE(2, vreg2) VSTORE(3, vreg3) }
; template <int D, bool WIN> ...
;     ...
;     float psum = 0.f;
; #pragma unroll
;     for (int kt = 0; kt < 2; ++kt)
; #pragma unroll
;       for (int i = 0; i < 16; ++i) {
;         float pv = __builtin_amdgcn_exp2f(fmaf(Sacc[kt][i], cexp, -mnew));
;         Sacc[kt][i] = pv;
;         psum += pv;
;       }
;     lrow = lrow * alpha + psum;
; #pragma unroll
;     for (int m = 0; m < NMT; ++m)
; #pragma unroll
;       for (int i = 0; i < 16; ++i) Oacc[m][i] *= alpha;
; #pragma unroll
;     for (int kt = 0; kt < 2; ++kt)
; #pragma unroll
;       for (int s = 0; s < 2; ++s) {
;         bf16x8 pf = pack8(Sacc[kt], s);
; #pragma unroll
;         for (int m = 0; m < NMT; ++m) {
;           if constexpr (EARLY) {
;             Oacc[m] = MFMA32(vfr[(kt * 2 + s) * 2 + (m & 1)], pf, Oacc[m]);
;           } else {
;             const u16* vp = sVp(st) + (m * 32 + r) * LV + kt * 32 + 16 * s + 4 * h;
;             s16x4 lo = *(const s16x4*)vp;
;             s16x4 hi = *(const s16x4*)(vp + 8);
;             bf16x8 a = __builtin_shufflevector(lo, hi, 0, 1, 2, 3, 4, 5, 6, 7);
;             Oacc[m] = MFMA32(a, pf, Oacc[m]);
;           }
;         }
;       }
;     LSTORE(st ^ 1)
	v_exp_f32_e32 v84, v84
	v_pk_mul_f32 v[52:53], v[52:53], v[128:129] op_sel_hi:[1,0]
	v_pk_mul_f32 v[50:51], v[50:51], v[128:129] op_sel_hi:[1,0]
	v_pk_mul_f32 v[48:49], v[48:49], v[128:129] op_sel_hi:[1,0]
	v_add_f32_e32 v86, v84, v85
	v_fma_f32 v85, v93, s37, -v220
	v_exp_f32_e32 v85, v85
	v_pk_mul_f32 v[46:47], v[46:47], v[128:129] op_sel_hi:[1,0]
	v_pk_mul_f32 v[44:45], v[44:45], v[128:129] op_sel_hi:[1,0]
	v_pk_mul_f32 v[42:43], v[42:43], v[128:129] op_sel_hi:[1,0]
	v_add_f32_e32 v86, v85, v86
	v_add_f32_e32 v86, v87, v86
	v_add_f32_e32 v92, v90, v86
	v_exp_f32_e32 v86, v64
	v_fma_f32 v64, v65, s37, -v220
	v_exp_f32_e32 v88, v64
	v_fma_f32 v64, v66, s37, -v220
	v_exp_f32_e32 v89, v64
	v_fma_f32 v64, v67, s37, -v220
	v_exp_f32_e32 v91, v64
	v_fma_f32 v64, v68, s37, -v220
	v_exp_f32_e32 v93, v64
	v_fma_f32 v64, v69, s37, -v220
	v_exp_f32_e32 v94, v64
	v_fma_f32 v64, v70, s37, -v220
	v_exp_f32_e32 v95, v64
	v_fma_f32 v64, v71, s37, -v220
	v_exp_f32_e32 v230, v64
	v_fma_f32 v64, v72, s37, -v220
	v_exp_f32_e32 v69, v64
	v_fma_f32 v64, v73, s37, -v220
	v_exp_f32_e32 v231, v64
	v_fma_f32 v64, v74, s37, -v220
	v_exp_f32_e32 v232, v64
	v_fma_f32 v64, v75, s37, -v220
	v_exp_f32_e32 v233, v64
	v_fma_f32 v64, v76, s37, -v220
	v_exp_f32_e32 v234, v64
	v_fma_f32 v64, v77, s37, -v220
	v_exp_f32_e32 v235, v64
	v_fma_f32 v64, v78, s37, -v220
	v_exp_f32_e32 v78, v64
	v_fma_f32 v64, v79, s37, -v220
	v_exp_f32_e32 v79, v64
	v_add_f32_e32 v64, v86, v92
	v_add_f32_e32 v64, v88, v64
	v_add_f32_e32 v64, v89, v64
	v_add_f32_e32 v64, v91, v64
	v_add_f32_e32 v64, v93, v64
	v_add_f32_e32 v64, v94, v64
	v_add_f32_e32 v64, v95, v64
	v_add_f32_e32 v64, v230, v64
	v_add_f32_e32 v64, v69, v64
	v_add_f32_e32 v64, v231, v64
	v_add_f32_e32 v64, v232, v64
	v_add_f32_e32 v64, v233, v64
	v_add_f32_e32 v64, v234, v64
	v_add_f32_e32 v64, v235, v64
	v_add_f32_e32 v64, v78, v64
	v_add_u32_e32 v92, s8, v211
	v_add_f32_e32 v68, v79, v64
	v_cvt_pk_bf16_f32 v64, v222, v223
	v_add_u32_e32 v222, 0x4000, v92
	ds_read2_b64 v[70:73], v222 offset0:128 offset1:130
	ds_read2_b64 v[74:77], v222 offset0:132 offset1:134
	v_cvt_pk_bf16_f32 v65, v224, v225
	v_cvt_pk_bf16_f32 v66, v226, v227
	v_cvt_pk_bf16_f32 v67, v228, v229
	v_add_u32_e32 v223, 0x5000, v92
	v_pk_mul_f32 v[40:41], v[40:41], v[128:129] op_sel_hi:[1,0]
	s_waitcnt lgkmcnt(1)
	v_mfma_f32_32x32x16_bf16 v[48:63], v[70:73], v[64:67], v[48:63]
	ds_read2_b64 v[70:73], v223 offset0:160 offset1:162
	s_waitcnt vmcnt(0)
	v_add3_u32 v252, s42, v216, v134
	ds_write_b128 v252, v[236:239]
	v_add3_u32 v252, s42, v217, v134
	ds_write_b128 v252, v[240:243]
	v_add3_u32 v252, s42, v218, v134
	ds_write_b128 v252, v[244:247]
	v_add3_u32 v252, s42, v219, v134
	ds_write_b128 v252, v[248:251]
	global_load_dwordx4 v[236:239], v[170:171], off
	global_load_dwordx4 v[240:243], v[168:169], off
	global_load_dwordx4 v[244:247], v[166:167], off
	global_load_dwordx4 v[248:251], v[164:165], off
	v_mul_f32_e64 v38, v38, v128
	v_mul_f32_e64 v39, v39, v128
	v_mul_f32_e64 v36, v36, v128
	v_mul_f32_e64 v37, v37, v128
	v_pk_mul_f32 v[34:35], v[34:35], v[128:129] op_sel_hi:[1,0]
	v_pk_mul_f32 v[32:33], v[32:33], v[128:129] op_sel_hi:[1,0]
	v_add_u32_e32 v224, 0x6000, v92
	v_pk_mul_f32 v[30:31], v[30:31], v[128:129] op_sel_hi:[1,0]
	s_waitcnt lgkmcnt(0)
	v_mfma_f32_32x32x16_bf16 v[32:47], v[70:73], v[64:67], v[32:47]
	ds_read2_b64 v[70:73], v224 offset0:192 offset1:194
	v_mul_f32_e64 v28, v28, v128
	v_mul_f32_e64 v29, v29, v128
	v_mul_f32_e64 v26, v26, v128
	v_mul_f32_e64 v27, v27, v128
	v_pk_mul_f32 v[24:25], v[24:25], v[128:129] op_sel_hi:[1,0]
	v_pk_mul_f32 v[22:23], v[22:23], v[128:129] op_sel_hi:[1,0]
	v_pk_mul_f32 v[20:21], v[20:21], v[128:129] op_sel_hi:[1,0]
	v_pk_mul_f32 v[18:19], v[18:19], v[128:129] op_sel_hi:[1,0]
	v_pk_mul_f32 v[16:17], v[16:17], v[128:129] op_sel_hi:[1,0]
	v_add_u32_e32 v92, 0x7000, v92
	v_pk_mul_f32 v[14:15], v[14:15], v[128:129] op_sel_hi:[1,0]
	s_waitcnt lgkmcnt(0)
	v_mfma_f32_32x32x16_bf16 v[16:31], v[70:73], v[64:67], v[16:31]
	ds_read2_b64 v[70:73], v92 offset0:224 offset1:226
	v_mul_f32_e64 v12, v12, v128
	v_mul_f32_e64 v13, v13, v128
	v_mul_f32_e64 v10, v10, v128
	v_mul_f32_e64 v11, v11, v128
	v_pk_mul_f32 v[8:9], v[8:9], v[128:129] op_sel_hi:[1,0]
	v_pk_mul_f32 v[6:7], v[6:7], v[128:129] op_sel_hi:[1,0]
	v_pk_mul_f32 v[4:5], v[4:5], v[128:129] op_sel_hi:[1,0]
	v_pk_mul_f32 v[2:3], v[2:3], v[128:129] op_sel_hi:[1,0]
	v_pk_mul_f32 v[0:1], v[0:1], v[128:129] op_sel_hi:[1,0]
	s_xor_b32 s8, s22, 1
	s_mul_i32 s8, s8, 0x8800
	s_waitcnt lgkmcnt(0)
	v_mfma_f32_32x32x16_bf16 v[0:15], v[70:73], v[64:67], v[0:15]
	ds_read2_b64 v[70:73], v223 offset0:164 offset1:166
	v_cvt_pk_bf16_f32 v64, v80, v81
	v_cvt_pk_bf16_f32 v65, v82, v83
	v_cvt_pk_bf16_f32 v66, v84, v85
	v_cvt_pk_bf16_f32 v67, v87, v90
	v_fmac_f32_e32 v68, v221, v128
	s_cmpk_lg_i32 s25, 0x140
	s_waitcnt lgkmcnt(0)
	v_mfma_f32_32x32x16_bf16 v[32:47], v[70:73], v[64:67], v[32:47]
	ds_read2_b64 v[70:73], v224 offset0:196 offset1:198
	s_waitcnt lgkmcnt(0)
	v_mfma_f32_32x32x16_bf16 v[16:31], v[70:73], v[64:67], v[16:31]
	ds_read2_b64 v[70:73], v92 offset0:228 offset1:230
	s_waitcnt lgkmcnt(0)
	v_mfma_f32_32x32x16_bf16 v[0:15], v[70:73], v[64:67], v[0:15]
	ds_read2_b64 v[70:73], v222 offset0:136 offset1:138
	v_mfma_f32_32x32x16_bf16 v[48:63], v[74:77], v[64:67], v[48:63]
	v_cvt_pk_bf16_f32 v64, v86, v88
	v_cvt_pk_bf16_f32 v65, v89, v91
	v_cvt_pk_bf16_f32 v66, v93, v94
	v_cvt_pk_bf16_f32 v67, v95, v230
	s_waitcnt lgkmcnt(0)
	s_nop 0
	v_mfma_f32_32x32x16_bf16 v[48:63], v[70:73], v[64:67], v[48:63]
	ds_read2_b64 v[70:73], v223 offset0:168 offset1:170
	s_waitcnt lgkmcnt(0)
; #define MFMA32(a, b, c) __builtin_amdgcn_mfma_f32_32x32x16_bf16((a), (b), (c), 0, 0, 0)
; #define LSTORE(stv) { const int st_ = (stv); KSTORE(0, kreg0) KSTORE(1, kreg1) KSTORE(2, kreg2) KSTORE(3, kreg3) \
;     VSTORE(0, vreg0) VSTORE(1, vreg1) VSTORE(2, vreg2) VSTORE(3, vreg3) }
; template <int D, bool WIN> ...
;     ...
;         for (int m = 0; m < NMT; ++m) {
;           if constexpr (EARLY) {
;             Oacc[m] = MFMA32(vfr[(kt * 2 + s) * 2 + (m & 1)], pf, Oacc[m]);
;           } else {
;             const u16* vp = sVp(st) + (m * 32 + r) * LV + kt * 32 + 16 * s + 4 * h;
;             s16x4 lo = *(const s16x4*)vp;
;             s16x4 hi = *(const s16x4*)(vp + 8);
;             bf16x8 a = __builtin_shufflevector(lo, hi, 0, 1, 2, 3, 4, 5, 6, 7);
;             Oacc[m] = MFMA32(a, pf, Oacc[m]);
;           }
;         }
;       }
;     LSTORE(st ^ 1)
;     __syncthreads();
;   }
;   const float ltot = lrow + __shfl_xor(lrow, 32);
;   const float inv = 1.0f / ltot;
;   u16* op = O + (size_t)(32 * w + r) * ldo;
;   float ssum = 0.f;
; #pragma unroll
;   for (int m = 0; m < NMT; ++m)
; #pragma unroll
;     for (int g = 0; g < 4; ++g) {
;       float a = Oacc[m][4 * g] * inv, b = Oacc[m][4 * g + 1] * inv, c = Oacc[m][4 * g + 2] * inv, d = Oacc[m][4 * g + 3] * inv;
;       ssum += a * a + b * b + c * c + d * d;
;       st4bf(op + 32 * m + 8 * g + 4 * h, a, b, c, d);
;     }
	v_mfma_f32_32x32x16_bf16 v[32:47], v[70:73], v[64:67], v[32:47]
	ds_read2_b64 v[70:73], v224 offset0:200 offset1:202
	s_waitcnt lgkmcnt(0)
	v_mfma_f32_32x32x16_bf16 v[16:31], v[70:73], v[64:67], v[16:31]
	ds_read2_b64 v[70:73], v92 offset0:232 offset1:234
	s_waitcnt lgkmcnt(0)
	v_mfma_f32_32x32x16_bf16 v[0:15], v[70:73], v[64:67], v[0:15]
	ds_read2_b64 v[70:73], v222 offset0:140 offset1:142
	v_cvt_pk_bf16_f32 v64, v69, v231
	v_cvt_pk_bf16_f32 v65, v232, v233
	v_cvt_pk_bf16_f32 v66, v234, v235
	v_cvt_pk_bf16_f32 v67, v78, v79
	v_add3_u32 v69, s8, v216, v134
	v_mov_b32_e32 v222, v220
	s_waitcnt lgkmcnt(0)
	v_mfma_f32_32x32x16_bf16 v[48:63], v[70:73], v[64:67], v[48:63]
	ds_read2_b64 v[70:73], v223 offset0:172 offset1:174
	s_waitcnt lgkmcnt(0)
	v_mfma_f32_32x32x16_bf16 v[32:47], v[70:73], v[64:67], v[32:47]
	ds_read2_b64 v[70:73], v224 offset0:204 offset1:206
	s_waitcnt lgkmcnt(0)
	v_mfma_f32_32x32x16_bf16 v[16:31], v[70:73], v[64:67], v[16:31]
	ds_read2_b64 v[70:73], v92 offset0:236 offset1:238
	s_waitcnt lgkmcnt(0)
	v_mfma_f32_32x32x16_bf16 v[0:15], v[70:73], v[64:67], v[0:15]
	s_waitcnt vmcnt(0)
	v_lshl_add_u32 v64, v192, 1, s8
	v_add3_u32 v69, v64, v144, s36
	ds_write2_b64 v69, v[236:237], v[238:239] offset1:1
	v_lshl_add_u32 v64, v193, 1, s8
	v_add3_u32 v69, v64, v144, s36
	ds_write2_b64 v69, v[240:241], v[242:243] offset1:1
	v_lshl_add_u32 v64, v194, 1, s8
	v_add3_u32 v69, v64, v144, s36
	ds_write2_b64 v69, v[244:245], v[246:247] offset1:1
	v_lshl_add_u32 v64, v196, 1, s8
	v_add3_u32 v69, v64, v144, s36
	ds_write2_b64 v69, v[248:249], v[250:251] offset1:1
	s_waitcnt lgkmcnt(0)
	s_barrier
	s_cbranch_scc1 .LBB0_326
	ds_bpermute_b32 v64, v209, v68
	s_lshl_b64 s[10:11], s[10:11], 1
	s_add_u32 s8, s34, s10
	s_addc_u32 s11, s35, s11
	s_add_u32 s10, s8, s20
	s_waitcnt lgkmcnt(0)
	v_add_f32_e32 v64, v68, v64
	v_div_scale_f32 v65, s[22:23], v64, v64, 1.0
	v_rcp_f32_e32 v66, v65
	s_addc_u32 s11, s11, s21
	v_lshlrev_b32_e32 v128, 1, v190
	s_add_i32 s38, s38, s12
	v_fma_f32 v67, -v65, v66, 1.0
	v_fmac_f32_e32 v66, v67, v66
	v_div_scale_f32 v67, vcc, 1.0, v64, 1.0
	v_mul_f32_e32 v68, v67, v66
	v_fma_f32 v69, -v65, v68, v67
	v_fmac_f32_e32 v68, v69, v66
	v_fma_f32 v65, -v65, v68, v67
	v_div_fmas_f32 v65, v65, v66, v68
	v_div_fixup_f32 v64, v65, v64, 1.0
	v_lshl_add_u64 v[66:67], s[10:11], 0, v[160:161]
	v_pk_mul_f32 v[48:49], v[48:49], v[64:65] op_sel_hi:[1,0]
	v_pk_mul_f32 v[50:51], v[50:51], v[64:65] op_sel_hi:[1,0]
	v_pk_mul_f32 v[32:33], v[32:33], v[64:65] op_sel_hi:[1,0]
	v_pk_mul_f32 v[34:35], v[34:35], v[64:65] op_sel_hi:[1,0]
	v_pk_mul_f32 v[16:17], v[16:17], v[64:65] op_sel_hi:[1,0]
	v_pk_mul_f32 v[18:19], v[18:19], v[64:65] op_sel_hi:[1,0]
	v_pk_mul_f32 v[0:1], v[0:1], v[64:65] op_sel_hi:[1,0]
	v_pk_mul_f32 v[2:3], v[2:3], v[64:65] op_sel_hi:[1,0]
	v_lshl_add_u64 v[66:67], v[66:67], 0, v[128:129]
	v_cvt_pk_bf16_f32 v48, v48, v49
	v_cvt_pk_bf16_f32 v49, v50, v51
	v_cvt_pk_bf16_f32 v32, v32, v33
	v_cvt_pk_bf16_f32 v33, v34, v35
	v_cvt_pk_bf16_f32 v16, v16, v17
	v_cvt_pk_bf16_f32 v17, v18, v19
	v_cvt_pk_bf16_f32 v0, v0, v1
	v_cvt_pk_bf16_f32 v1, v2, v3
	global_store_dwordx2 v[66:67], v[48:49], off
	v_pk_mul_f32 v[48:49], v[52:53], v[64:65] op_sel_hi:[1,0]
	v_pk_mul_f32 v[50:51], v[54:55], v[64:65] op_sel_hi:[1,0]
	global_store_dwordx2 v[66:67], v[32:33], off offset:64
	v_pk_mul_f32 v[32:33], v[36:37], v[64:65] op_sel_hi:[1,0]
	v_pk_mul_f32 v[34:35], v[38:39], v[64:65] op_sel_hi:[1,0]
	global_store_dwordx2 v[66:67], v[16:17], off offset:128
	v_pk_mul_f32 v[16:17], v[20:21], v[64:65] op_sel_hi:[1,0]
	v_pk_mul_f32 v[18:19], v[22:23], v[64:65] op_sel_hi:[1,0]
	global_store_dwordx2 v[66:67], v[0:1], off offset:192
	v_pk_mul_f32 v[0:1], v[4:5], v[64:65] op_sel_hi:[1,0]
	v_pk_mul_f32 v[2:3], v[6:7], v[64:65] op_sel_hi:[1,0]
	v_cvt_pk_bf16_f32 v48, v48, v49
	v_cvt_pk_bf16_f32 v49, v50, v51
	v_cvt_pk_bf16_f32 v32, v32, v33
	v_cvt_pk_bf16_f32 v33, v34, v35
	v_cvt_pk_bf16_f32 v16, v16, v17
	v_cvt_pk_bf16_f32 v17, v18, v19
	v_cvt_pk_bf16_f32 v0, v0, v1
	v_cvt_pk_bf16_f32 v1, v2, v3
	global_store_dwordx2 v[66:67], v[48:49], off offset:16
	v_pk_mul_f32 v[48:49], v[56:57], v[64:65] op_sel_hi:[1,0]
	v_pk_mul_f32 v[50:51], v[58:59], v[64:65] op_sel_hi:[1,0]
	global_store_dwordx2 v[66:67], v[32:33], off offset:80
	v_pk_mul_f32 v[32:33], v[40:41], v[64:65] op_sel_hi:[1,0]
	v_pk_mul_f32 v[34:35], v[42:43], v[64:65] op_sel_hi:[1,0]
	global_store_dwordx2 v[66:67], v[16:17], off offset:144
	v_pk_mul_f32 v[16:17], v[24:25], v[64:65] op_sel_hi:[1,0]
	v_pk_mul_f32 v[18:19], v[26:27], v[64:65] op_sel_hi:[1,0]
	global_store_dwordx2 v[66:67], v[0:1], off offset:208
	v_pk_mul_f32 v[0:1], v[8:9], v[64:65] op_sel_hi:[1,0]
	v_pk_mul_f32 v[2:3], v[10:11], v[64:65] op_sel_hi:[1,0]
	v_cvt_pk_bf16_f32 v48, v48, v49
	v_cvt_pk_bf16_f32 v49, v50, v51
	v_cvt_pk_bf16_f32 v32, v32, v33
	v_cvt_pk_bf16_f32 v33, v34, v35
	v_cvt_pk_bf16_f32 v16, v16, v17
	v_cvt_pk_bf16_f32 v17, v18, v19
	v_cvt_pk_bf16_f32 v0, v0, v1
	v_cvt_pk_bf16_f32 v1, v2, v3
	global_store_dwordx2 v[66:67], v[48:49], off offset:32
	v_pk_mul_f32 v[48:49], v[60:61], v[64:65] op_sel_hi:[1,0]
	v_pk_mul_f32 v[50:51], v[62:63], v[64:65] op_sel_hi:[1,0]
	global_store_dwordx2 v[66:67], v[32:33], off offset:96
	v_pk_mul_f32 v[32:33], v[44:45], v[64:65] op_sel_hi:[1,0]
	v_pk_mul_f32 v[34:35], v[46:47], v[64:65] op_sel_hi:[1,0]
	global_store_dwordx2 v[66:67], v[16:17], off offset:160
	v_pk_mul_f32 v[16:17], v[28:29], v[64:65] op_sel_hi:[1,0]
	v_pk_mul_f32 v[18:19], v[30:31], v[64:65] op_sel_hi:[1,0]
	global_store_dwordx2 v[66:67], v[0:1], off offset:224
	v_pk_mul_f32 v[0:1], v[12:13], v[64:65] op_sel_hi:[1,0]
	v_pk_mul_f32 v[2:3], v[14:15], v[64:65] op_sel_hi:[1,0]
	v_cvt_pk_bf16_f32 v48, v48, v49
	v_cvt_pk_bf16_f32 v49, v50, v51
	v_cvt_pk_bf16_f32 v32, v32, v33
	v_cvt_pk_bf16_f32 v33, v34, v35
	v_cvt_pk_bf16_f32 v16, v16, v17
	v_cvt_pk_bf16_f32 v17, v18, v19
	v_cvt_pk_bf16_f32 v0, v0, v1
	v_cvt_pk_bf16_f32 v1, v2, v3
	s_cmpk_lt_i32 s38, 0xc00
	global_store_dwordx2 v[66:67], v[48:49], off offset:48
	global_store_dwordx2 v[66:67], v[32:33], off offset:112
	global_store_dwordx2 v[66:67], v[16:17], off offset:176
	global_store_dwordx2 v[66:67], v[0:1], off offset:240
	s_barrier
	s_cbranch_scc1 .LBB0_321
